# EPI_M 8-phase loop switched to SGPR-base + 32-bit offset LDS-DMA pieces (same generator as the other GEMM loops)
# speedup vs baseline: 1.0090x; 1.0090x over previous
; template <bool SWAP>
; DI void gemm_mainloop(f32x16 (&acc)[4][2], const u16* __restrict__ A, int lda, int rlo, int rhi,
;                       const u16* __restrict__ B, int ldb, int K, char* lds, const u16* zero_line) {
;     ...
;   const int gch = (lc ^ ((lr >> 1) & 7)) * 8;
;   const u16* ap = A + (ptrdiff_t)lr * lda + gch;
;   const u16* bp = B + (ptrdiff_t)lr * ldb + gch;
;   const int nk = K >> 6;
;   typedef __attribute__((address_space(3))) unsigned lds_u32;
;   auto glds = [&](int kt, int st) {
;     char* as_ = lds + st * 65536 + tid * 16;
; #pragma unroll
;     for (int i = 0; i < 4; ++i) {
;       const int rr = lr + 64 * i;
;       const u16* srca = (rr >= rlo && rr < rhi) ? (ap + (ptrdiff_t)(64 * i) * lda + kt * 64) : (zero_line + lc * 8);
;       __builtin_amdgcn_global_load_lds((const unsigned*)srca, (lds_u32*)(as_ + i * 8192), 16, 0, 0);
;       __builtin_amdgcn_global_load_lds((const unsigned*)(bp + (ptrdiff_t)(64 * i) * ldb + kt * 64), (lds_u32*)(as_ + 32768 + i * 8192), 16, 0, 0);
;     }
;   };
;   const int sw = (r >> 1) & 7;
;   const int arow_off = (wm * 128 + r) * 128;
;   const int brow_off = 32768 + (wn * 64 + r) * 128;
;   __syncthreads();
;   glds(0, 0);
;   asm volatile("s_waitcnt vmcnt(0)" ::: "memory");
;   __syncthreads();
; template <int EPI>
; DI void phase_gemm(const Params& p, const GemmArgs& ga, char* lds) {
;     ...
;   for (int it = 0; it * (int)gridDim.x < total; ++it) {
;     const int lt = logical_index(it);
;     if (lt >= total) continue;
;     int mt, nt;
;     tile_mn(lt, Mt, ga.Nt, mt, nt);
;     int bb, tokbase, S, pos0, rlo = 0, rhi = 256;
;     if (EPI == EPI_UP) {
;       bb = 0; tokbase = 0; S = NTOK;
;       pos0 = 254 * mt - 1;
;       rlo = (mt == 0) ? 1 : 0;
;       rhi = NTOK - pos0; if (rhi > 256) rhi = 256;
;     } else {
;       seq_of_token(mt * 256, bb, tokbase, S);
;       pos0 = mt * 256 - tokbase;
;     }
;     const u16* A = ga.A + (ptrdiff_t)(tokbase + pos0) * ga.lda;
;     const u16* B = ga.Bt + (size_t)(nt * 256) * ga.K;
.LBB0_244:
	s_add_i32 s6, s6, s27
	s_cmpk_gt_i32 s6, 0x2ff
	s_cbranch_scc1 .LBB0_243
	s_ashr_i32 s7, s6, 31
	s_lshr_b32 s7, s7, 27
	s_add_i32 s7, s6, s7
	s_ashr_i32 s35, s7, 5
	s_andn2_b32 s7, s7, 31
	s_sub_i32 s6, s6, s7
	s_ashr_i32 s7, s6, 31
	s_lshr_b32 s7, s7, 29
	s_add_i32 s7, s6, s7
	s_ashr_i32 s7, s7, 3
	s_lshl_b32 s8, s35, 11
	s_lshl_b32 s6, s6, 8
	s_lshl_b32 s24, s7, 8
	s_add_i32 s6, s6, s8
	s_lshl_b32 s36, s7, 11
	s_ashr_i32 s25, s24, 31
	s_sub_i32 s34, s6, s36
	s_mul_i32 s6, s25, s98
	s_mul_hi_u32 s7, s24, s98
	s_add_i32 s7, s7, s6
	s_mul_i32 s6, s24, s98
	s_lshl_b64 s[6:7], s[6:7], 1
	s_add_u32 s6, s16, s6
	v_mov_b32_e32 v10, v204
	s_addc_u32 s7, s17, s7
	s_ashr_i32 s8, s34, 31
	s_mul_i32 s8, s8, s98
	v_ashrrev_i32_e32 v2, 3, v10
	s_mul_hi_u32 s9, s34, s98
	v_mad_u64_u32 v[4:5], s[10:11], v2, s98, 0
	s_add_i32 s9, s9, s8
	s_mul_i32 s8, s34, s98
	v_ashrrev_i32_e32 v3, 31, v2
	v_mov_b32_e32 v0, v5
	s_lshl_b64 s[8:9], s[8:9], 1
	v_lshrrev_b32_e32 v12, 1, v2
	v_mad_u64_u32 v[6:7], s[10:11], v3, s98, v[0:1]
	s_add_u32 s8, s12, s8
	v_xor_b32_e32 v9, v12, v10
	v_mov_b32_e32 v5, v6
	s_addc_u32 s9, s13, s9
	v_lshlrev_b64 v[4:5], 1, v[4:5]
	v_lshlrev_b32_e32 v0, 4, v9
	v_and_b32_e32 v8, 31, v10
	v_lshl_add_u64 v[6:7], s[8:9], 0, v[4:5]
	v_and_b32_e32 v0, 0x70, v0
	v_lshl_add_u64 v[4:5], s[6:7], 0, v[4:5]
	v_lshrrev_b32_e32 v13, 1, v10
	v_lshl_add_u64 v[6:7], v[6:7], 0, v[0:1]
	v_lshl_add_u64 v[4:5], v[4:5], 0, v[0:1]
	v_and_or_b32 v0, v13, s51, v8
	v_lshlrev_b32_e32 v203, 7, v0
	v_lshlrev_b32_e32 v0, 7, v10
	v_lshlrev_b32_e32 v226, 4, v10
	v_and_b32_e32 v202, 0x6f80, v0
	v_and_b32_e32 v0, 0x70, v226
	v_add_u32_e32 v15, 0x8000, v226
	v_lshl_add_u64 v[180:181], s[80:81], 0, v[0:1]
	v_cmp_gt_u32_e32 vcc, s50, v2
	v_readfirstlane_b32 s6, v226
	s_mov_b32 m0, s6
	v_cndmask_b32_e32 v9, v181, v7, vcc
	v_cndmask_b32_e32 v8, v180, v6, vcc
	v_readfirstlane_b32 s6, v15
	v_add_u32_e32 v0, 64, v2
	s_barrier
	s_mov_b32 m0, s6
	v_cmp_gt_u32_e64 s[6:7], s50, v0
	v_add_u32_e32 v0, 0x2000, v226
	v_lshl_add_u64 v[6:7], v[6:7], 0, s[18:19]
	v_readfirstlane_b32 s8, v0
	v_add_u32_e32 v0, 0xa000, v226
	v_cndmask_b32_e64 v9, v181, v7, s[6:7]
	v_cndmask_b32_e64 v8, v180, v6, s[6:7]
	s_mov_b32 m0, s8
	v_readfirstlane_b32 s8, v0
	v_add_u32_e32 v0, 0x80, v2
	s_mov_b32 m0, s8
	v_cmp_gt_u32_e64 s[8:9], s50, v0
	v_add_u32_e32 v0, 0x4000, v226
	v_lshl_add_u64 v[4:5], v[4:5], 0, s[18:19]
	v_lshl_add_u64 v[6:7], v[6:7], 0, s[18:19]
	v_readfirstlane_b32 s10, v0
	v_add_u32_e32 v0, 0xc000, v226
	v_cndmask_b32_e64 v9, v181, v7, s[8:9]
	v_cndmask_b32_e64 v8, v180, v6, s[8:9]
	s_mov_b32 m0, s10
	v_readfirstlane_b32 s10, v0
	v_add_u32_e32 v0, 0xc0, v2
	s_mov_b32 m0, s10
	v_cmp_gt_u32_e64 s[10:11], s50, v0
	v_add_u32_e32 v0, 0x6000, v226
	v_lshl_add_u64 v[4:5], v[4:5], 0, s[18:19]
	v_lshl_add_u64 v[6:7], v[6:7], 0, s[18:19]
	v_readfirstlane_b32 s37, v0
	v_add_u32_e32 v0, 0xe000, v226
	v_cndmask_b32_e64 v7, v181, v7, s[10:11]
	v_cndmask_b32_e64 v6, v180, v6, s[10:11]
	s_mov_b32 m0, s37
	v_readfirstlane_b32 s37, v0
	v_lshl_add_u64 v[4:5], v[4:5], 0, s[18:19]
	s_mov_b32 m0, s37
	s_sub_i32 s36, s29, s36
	s_mulk_i32 s35, 0x1800
	s_sub_i32 s36, s36, s35
	s_ashr_i32 s37, s36, 31
	v_lshlrev_b64 v[2:3], 1, v[2:3]
	s_lshl_b64 s[36:37], s[36:37], 1
	v_lshl_add_u64 v[4:5], v[2:3], 0, s[36:37]
	v_mov_b64_e32 v[6:7], s[20:21]
	v_mad_u64_u32 v[182:183], s[38:39], s98, v4, v[6:7]
	v_mov_b32_e32 v4, v183
	v_mad_u64_u32 v[4:5], s[38:39], s98, v5, v[4:5]
	s_lshl_b64 s[38:39], s[24:25], 1
	v_bfe_u32 v11, v10, 5, 1
	v_mov_b32_e32 v183, v4
	v_lshl_add_u64 v[4:5], v[2:3], 0, s[38:39]
	v_mov_b64_e32 v[8:9], s[22:23]
	v_bfe_u32 v14, v10, 1, 3
	v_bitop3_b32 v0, v13, v11, 7 bitop3:0x6c
	v_mad_u64_u32 v[186:187], s[40:41], s98, v4, v[8:9]
	v_lshlrev_b32_e32 v228, 4, v0
	v_bitop3_b32 v0, v11, v14, 2 bitop3:0x36
	v_mov_b32_e32 v4, v187
	v_lshlrev_b32_e32 v227, 4, v0
	v_bitop3_b32 v0, v11, v14, 4 bitop3:0x36
	v_mad_u64_u32 v[4:5], s[40:41], s98, v5, v[4:5]
	v_lshlrev_b32_e32 v201, 4, v0
	v_bitop3_b32 v0, v11, v14, 6 bitop3:0x36
	v_mov_b32_e32 v187, v4
	v_lshl_add_u64 v[4:5], v[2:3], 0, s[4:5]
	v_lshlrev_b32_e32 v179, 4, v0
	v_bitop3_b32 v0, v12, 7, v10 bitop3:0x48
	v_lshl_add_u64 v[10:11], v[4:5], 0, s[36:37]
	v_lshl_add_u64 v[4:5], v[4:5], 0, s[38:39]
	v_mad_u64_u32 v[188:189], s[40:41], s98, v10, v[6:7]
	v_mad_u64_u32 v[190:191], s[40:41], s98, v4, v[8:9]
	v_mov_b32_e32 v10, v189
	v_mov_b32_e32 v4, v191
	v_mad_u64_u32 v[10:11], s[40:41], s98, v11, v[10:11]
	v_mad_u64_u32 v[4:5], s[40:41], s98, v5, v[4:5]
	s_mov_b64 s[40:41], 0x100
	v_mov_b32_e32 v191, v4
	v_lshl_add_u64 v[4:5], v[2:3], 0, s[40:41]
	v_mov_b32_e32 v189, v10
	v_lshl_add_u64 v[10:11], v[4:5], 0, s[36:37]
	v_lshl_add_u64 v[4:5], v[4:5], 0, s[38:39]
	v_mad_u64_u32 v[192:193], s[40:41], s98, v10, v[6:7]
	v_mad_u64_u32 v[194:195], s[40:41], s98, v4, v[8:9]
	v_mov_b32_e32 v10, v193
	v_mov_b32_e32 v4, v195
	v_mad_u64_u32 v[10:11], s[40:41], s98, v11, v[10:11]
	v_mad_u64_u32 v[4:5], s[40:41], s98, v5, v[4:5]
	s_mov_b64 s[40:41], 0x180
	s_nop 0
	v_lshl_add_u64 v[2:3], v[2:3], 0, s[40:41]
	v_mov_b32_e32 v195, v4
	v_lshl_add_u64 v[4:5], v[2:3], 0, s[36:37]
	v_lshl_add_u64 v[2:3], v[2:3], 0, s[38:39]
	v_mad_u64_u32 v[198:199], s[36:37], s98, v2, v[8:9]
	v_mad_u64_u32 v[196:197], s[36:37], s98, v4, v[6:7]
	v_mov_b32_e32 v2, v199
	s_waitcnt vmcnt(0)
; template <bool SWAP>
; DI void gemm_mainloop(f32x16 (&acc)[4][2], const u16* __restrict__ A, int lda, int rlo, int rhi,
;                       const u16* __restrict__ B, int ldb, int K, char* lds, const u16* zero_line) {
;     ...
; #pragma unroll
;   for (int mi = 0; mi < 4; ++mi)
; #pragma unroll
;     for (int ni = 0; ni < 2; ++ni)
; #pragma unroll
;       for (int i = 0; i < 16; ++i) acc[mi][ni][i] = 0.f;
;   const int gch = (lc ^ ((lr >> 1) & 7)) * 8;
;   const u16* ap = A + (ptrdiff_t)lr * lda + gch;
;   const u16* bp = B + (ptrdiff_t)lr * ldb + gch;
;   const int nk = K >> 6;
;   typedef __attribute__((address_space(3))) unsigned lds_u32;
;   auto glds = [&](int kt, int st) {
;     char* as_ = lds + st * 65536 + tid * 16;
; #pragma unroll
;     for (int i = 0; i < 4; ++i) {
;       const int rr = lr + 64 * i;
;       const u16* srca = (rr >= rlo && rr < rhi) ? (ap + (ptrdiff_t)(64 * i) * lda + kt * 64) : (zero_line + lc * 8);
;       __builtin_amdgcn_global_load_lds((const unsigned*)srca, (lds_u32*)(as_ + i * 8192), 16, 0, 0);
;       __builtin_amdgcn_global_load_lds((const unsigned*)(bp + (ptrdiff_t)(64 * i) * ldb + kt * 64), (lds_u32*)(as_ + 32768 + i * 8192), 16, 0, 0);
;     }
;   };
;   const int sw = (r >> 1) & 7;
;   const int arow_off = (wm * 128 + r) * 128;
;   const int brow_off = 32768 + (wn * 64 + r) * 128;
;   __syncthreads();
;   glds(0, 0);
;   asm volatile("s_waitcnt vmcnt(0)" ::: "memory");
;   __syncthreads();
;   bf16x8 fa[2][4], fb[2][2];
; #pragma unroll
;   for (int mi = 0; mi < 4; ++mi)
; #pragma unroll
;     for (int e = 0; e < 8; ++e) fa[1][mi][e] = 0;
; #pragma unroll
;   for (int ni = 0; ni < 2; ++ni)
; #pragma unroll
;     for (int e = 0; e < 8; ++e) fb[1][ni][e] = 0;
	v_mov_b32_e32 v4, v197
	v_mad_u64_u32 v[2:3], s[36:37], s98, v3, v[2:3]
	v_mad_u64_u32 v[4:5], s[36:37], s98, v5, v[4:5]
	v_mov_b32_e32 v199, v2
	v_mov_b32_e32 v130, 0
	v_mov_b32_e32 v2, 0
	v_lshlrev_b32_e32 v0, 4, v0
	v_mov_b32_e32 v193, v10
	v_mov_b32_e32 v197, v4
	s_mov_b32 s25, 0x10000
	v_mov_b32_e32 v3, v2
	v_mov_b32_e32 v4, v2
	v_mov_b32_e32 v5, v2
	v_mov_b32_e32 v6, v2
	v_mov_b32_e32 v7, v2
	v_mov_b32_e32 v8, v2
	v_mov_b32_e32 v9, v2
	v_mov_b32_e32 v10, v2
	v_mov_b32_e32 v11, v2
	v_mov_b32_e32 v12, v2
	v_mov_b32_e32 v13, v2
	v_mov_b32_e32 v14, v2
	v_mov_b32_e32 v15, v2
	v_mov_b32_e32 v16, v2
	v_mov_b32_e32 v17, v2
	v_mov_b32_e32 v18, v2
	v_mov_b32_e32 v19, v2
	v_mov_b32_e32 v20, v2
	v_mov_b32_e32 v21, v2
	v_mov_b32_e32 v22, v2
	v_mov_b32_e32 v23, v2
	v_mov_b32_e32 v24, v2
	v_mov_b32_e32 v25, v2
	v_mov_b32_e32 v26, v2
	v_mov_b32_e32 v27, v2
	v_mov_b32_e32 v28, v2
	v_mov_b32_e32 v29, v2
	v_mov_b32_e32 v30, v2
	v_mov_b32_e32 v31, v2
	v_mov_b32_e32 v32, v2
	v_mov_b32_e32 v33, v2
	v_mov_b32_e32 v34, v2
	v_mov_b32_e32 v35, v2
	v_mov_b32_e32 v36, v2
	v_mov_b32_e32 v37, v2
	v_mov_b32_e32 v38, v2
	v_mov_b32_e32 v39, v2
	v_mov_b32_e32 v40, v2
	v_mov_b32_e32 v41, v2
	v_mov_b32_e32 v42, v2
	v_mov_b32_e32 v43, v2
	v_mov_b32_e32 v44, v2
	v_mov_b32_e32 v45, v2
	v_mov_b32_e32 v46, v2
	v_mov_b32_e32 v47, v2
	v_mov_b32_e32 v48, v2
	v_mov_b32_e32 v49, v2
	v_mov_b32_e32 v50, v2
	v_mov_b32_e32 v51, v2
	v_mov_b32_e32 v52, v2
	v_mov_b32_e32 v53, v2
	v_mov_b32_e32 v54, v2
	v_mov_b32_e32 v55, v2
	v_mov_b32_e32 v56, v2
	v_mov_b32_e32 v57, v2
	v_mov_b32_e32 v58, v2
	v_mov_b32_e32 v59, v2
	v_mov_b32_e32 v60, v2
	v_mov_b32_e32 v61, v2
	v_mov_b32_e32 v62, v2
	v_mov_b32_e32 v63, v2
	v_mov_b32_e32 v64, v2
	v_mov_b32_e32 v65, v2
	v_mov_b32_e32 v66, v2
	v_mov_b32_e32 v67, v2
	v_mov_b32_e32 v68, v2
	v_mov_b32_e32 v69, v2
	v_mov_b32_e32 v70, v2
	v_mov_b32_e32 v71, v2
	v_mov_b32_e32 v72, v2
	v_mov_b32_e32 v73, v2
	v_mov_b32_e32 v74, v2
	v_mov_b32_e32 v75, v2
	v_mov_b32_e32 v76, v2
	v_mov_b32_e32 v77, v2
	v_mov_b32_e32 v78, v2
	v_mov_b32_e32 v79, v2
	v_mov_b32_e32 v80, v2
	v_mov_b32_e32 v81, v2
	v_mov_b32_e32 v82, v2
	v_mov_b32_e32 v83, v2
	v_mov_b32_e32 v84, v2
	v_mov_b32_e32 v85, v2
	v_mov_b32_e32 v86, v2
	v_mov_b32_e32 v87, v2
	v_mov_b32_e32 v88, v2
	v_mov_b32_e32 v89, v2
	v_mov_b32_e32 v90, v2
	v_mov_b32_e32 v91, v2
	v_mov_b32_e32 v92, v2
	v_mov_b32_e32 v93, v2
	v_mov_b32_e32 v94, v2
	v_mov_b32_e32 v95, v2
	v_mov_b32_e32 v96, v2
	v_mov_b32_e32 v97, v2
	v_mov_b32_e32 v98, v2
	v_mov_b32_e32 v99, v2
	v_mov_b32_e32 v100, v2
	v_mov_b32_e32 v101, v2
	v_mov_b32_e32 v102, v2
	v_mov_b32_e32 v103, v2
	v_mov_b32_e32 v104, v2
	v_mov_b32_e32 v105, v2
	v_mov_b32_e32 v106, v2
	v_mov_b32_e32 v107, v2
	v_mov_b32_e32 v108, v2
	v_mov_b32_e32 v109, v2
	v_mov_b32_e32 v110, v2
	v_mov_b32_e32 v111, v2
	v_mov_b32_e32 v112, v2
	v_mov_b32_e32 v113, v2
	v_mov_b32_e32 v114, v2
	v_mov_b32_e32 v115, v2
	v_mov_b32_e32 v116, v2
	v_mov_b32_e32 v117, v2
	v_mov_b32_e32 v118, v2
	v_mov_b32_e32 v119, v2
	v_mov_b32_e32 v120, v2
	v_mov_b32_e32 v121, v2
	v_mov_b32_e32 v122, v2
	v_mov_b32_e32 v123, v2
	v_mov_b32_e32 v124, v2
	v_mov_b32_e32 v125, v2
	v_mov_b32_e32 v126, v2
	v_mov_b32_e32 v127, v2
	v_mov_b32_e32 v128, v2
	v_mov_b32_e32 v129, v2
	v_mov_b32_e32 v131, v130
	v_mov_b32_e32 v132, v130
	v_mov_b32_e32 v133, v130
	v_mov_b32_e32 v134, v130
	v_mov_b32_e32 v135, v130
	v_mov_b32_e32 v136, v130
	v_mov_b32_e32 v137, v130
	v_mov_b32_e32 v142, v130
	v_mov_b32_e32 v143, v130
	v_mov_b32_e32 v144, v130
	v_mov_b32_e32 v145, v130
	v_mov_b32_e32 v150, v130
	v_mov_b32_e32 v151, v130
	v_mov_b32_e32 v152, v130
	v_mov_b32_e32 v153, v130
	v_mov_b32_e32 v138, v130
	v_mov_b32_e32 v139, v130
	v_mov_b32_e32 v140, v130
	v_mov_b32_e32 v141, v130
	v_mov_b32_e32 v146, v130
	v_mov_b32_e32 v147, v130
	v_mov_b32_e32 v148, v130
	v_mov_b32_e32 v149, v130
	s_waitcnt vmcnt(0) lgkmcnt(0)
	s_barrier
	s_mul_i32 s6, s34, s98
	s_mul_hi_u32 s7, s34, s98
	s_lshl_b64 s[6:7], s[6:7], 1
	s_add_u32 s6, s12, s6
	s_addc_u32 s7, s13, s7
	s_mul_i32 s8, s24, s98
	s_mul_hi_u32 s9, s24, s98
	s_lshl_b64 s[8:9], s[8:9], 1
	s_add_u32 s8, s16, s8
	s_addc_u32 s9, s17, s9
	v_and_b32_e32 v130, 63, v204
	v_lshrrev_b32_e32 v131, 6, v204
	v_lshrrev_b32_e32 v132, 3, v204
	v_lshrrev_b32_e32 v0, 4, v130
	v_lshl_add_u32 v0, v131, 2, v0
	v_xor_b32_e32 v0, v0, v130
	v_and_b32_e32 v0, 7, v0
	v_lshlrev_b32_e32 v133, 4, v0
	v_mul_lo_u32 v0, v132, s98
	v_lshl_add_u32 v228, v0, 1, v133
	s_lshl_b32 s28, s98, 7
	v_add_u32_e32 v229, s28, v228
	v_add_u32_e32 v230, s28, v229
	v_add_u32_e32 v231, s28, v230
	v_and_b32_e32 v0, 31, v132
	v_lshrrev_b32_e32 v130, 5, v132
	v_lshl_add_u32 v0, v130, 6, v0
	v_mul_lo_u32 v0, v0, s98
	v_lshl_add_u32 v232, v0, 1, v133
	s_lshl_b32 s28, s98, 6
	v_add_u32_e32 v233, s28, v232
	s_lshl_b32 s28, s98, 8
	v_add_u32_e32 v234, s28, v232
	v_add_u32_e32 v235, s28, v233
	s_lshr_b32 s25, s98, 6
	s_add_i32 s25, s25, -2
	v_and_b32_e32 v132, 31, v204
	v_lshrrev_b32_e32 v0, 2, v131
	v_lshl_add_u32 v0, v0, 6, v132
	v_lshlrev_b32_e32 v240, 7, v0
	v_and_b32_e32 v0, 3, v131
	v_lshl_add_u32 v0, v0, 5, v132
	v_lshlrev_b32_e32 v241, 7, v0
	v_bfe_u32 v0, v204, 5, 1
	v_bfe_u32 v130, v132, 1, 3
	v_or_b32_e32 v133, 0, v0
	v_xor_b32_e32 v133, v133, v130
	v_lshlrev_b32_e32 v236, 4, v133
	v_or_b32_e32 v133, 2, v0
	v_xor_b32_e32 v133, v133, v130
	v_lshlrev_b32_e32 v237, 4, v133
	v_or_b32_e32 v133, 4, v0
	v_xor_b32_e32 v133, v133, v130
	v_lshlrev_b32_e32 v238, 4, v133
	v_or_b32_e32 v133, 6, v0
	v_xor_b32_e32 v133, v133, v130
	v_lshlrev_b32_e32 v239, 4, v133
	v_lshlrev_b32_e32 v131, 10, v131
	s_nop 0
	v_readfirstlane_b32 s100, v131
	v_mov_b32_e32 v146, 0
	v_mov_b32_e32 v147, 0
	v_mov_b32_e32 v148, 0
	v_mov_b32_e32 v149, 0
	v_lshlrev_b32_e32 v130, 4, v204
	v_add_u32_e32 v132, 0x10000, v130
	s_mov_b64 exec, -1
	s_mov_b32 s11, 0
	s_mov_b32 s10, 0x10000
	s_waitcnt lgkmcnt(0)
	s_add_u32 m0, s100, 0x8000
	s_nop 0
	global_load_lds_dwordx4 v232, s[8:9]
	v_add_u32_e32 v232, 0x80, v232
	s_add_u32 m0, s100, 0xa000
	s_nop 0
	global_load_lds_dwordx4 v234, s[8:9]
	v_add_u32_e32 v234, 0x80, v234
	s_add_u32 m0, s100, 0x0
	s_nop 0
	global_load_lds_dwordx4 v228, s[6:7]
	v_add_u32_e32 v228, 0x80, v228
	s_add_u32 m0, s100, 0x2000
	s_nop 0
	global_load_lds_dwordx4 v230, s[6:7]
	v_add_u32_e32 v230, 0x80, v230
	s_add_u32 m0, s100, 0xc000
	s_nop 0
	global_load_lds_dwordx4 v233, s[8:9]
	v_add_u32_e32 v233, 0x80, v233
	s_add_u32 m0, s100, 0xe000
	s_nop 0
	global_load_lds_dwordx4 v235, s[8:9]
	v_add_u32_e32 v235, 0x80, v235
	s_add_u32 m0, s100, 0x4000
	s_nop 0
	global_load_lds_dwordx4 v229, s[6:7]
	v_add_u32_e32 v229, 0x80, v229
	s_add_u32 m0, s100, 0x6000
	s_nop 0
	global_load_lds_dwordx4 v231, s[6:7]
	v_add_u32_e32 v231, 0x80, v231
	s_cmp_eq_u32 s101, 1
	s_cbranch_scc0 .Lg8_m246_p0
	s_barrier
; template <bool SWAP>
; DI void gemm_mainloop(f32x16 (&acc)[4][2], const u16* __restrict__ A, int lda, int rlo, int rhi,
;                       const u16* __restrict__ B, int ldb, int K, char* lds, const u16* zero_line) {
;     ...
;   auto glds = [&](int kt, int st) {
;     char* as_ = lds + st * 65536 + tid * 16;
; #pragma unroll
;     for (int i = 0; i < 4; ++i) {
;       const int rr = lr + 64 * i;
;       const u16* srca = (rr >= rlo && rr < rhi) ? (ap + (ptrdiff_t)(64 * i) * lda + kt * 64) : (zero_line + lc * 8);
;       __builtin_amdgcn_global_load_lds((const unsigned*)srca, (lds_u32*)(as_ + i * 8192), 16, 0, 0);
;       __builtin_amdgcn_global_load_lds((const unsigned*)(bp + (ptrdiff_t)(64 * i) * ldb + kt * 64), (lds_u32*)(as_ + 32768 + i * 8192), 16, 0, 0);
;     }
;   };
;   const int sw = (r >> 1) & 7;
;   const int arow_off = (wm * 128 + r) * 128;
;   const int brow_off = 32768 + (wn * 64 + r) * 128;
;   __syncthreads();
;   glds(0, 0);
;   asm volatile("s_waitcnt vmcnt(0)" ::: "memory");
;   __syncthreads();
;   bf16x8 fa[2][4], fb[2][2];
; #pragma unroll
;   for (int mi = 0; mi < 4; ++mi)
; #pragma unroll
;     for (int e = 0; e < 8; ++e) fa[1][mi][e] = 0;
; #pragma unroll
;   for (int ni = 0; ni < 2; ++ni)
; #pragma unroll
;     for (int e = 0; e < 8; ++e) fb[1][ni][e] = 0;
;   auto ldfrag = [&](const char* st, int ks, int buf) {
;     const int co = ((2 * ks + h) ^ sw) << 4;
; #pragma unroll
;     for (int mi = 0; mi < 4; ++mi) fa[buf][mi] = *(const bf16x8*)(st + arow_off + mi * 4096 + co);
; #pragma unroll
;     for (int ni = 0; ni < 2; ++ni) fb[buf][ni] = *(const bf16x8*)(st + brow_off + ni * 4096 + co);
;   };
;   auto mma = [&](int buf) {
; #pragma unroll
;     for (int mi = 0; mi < 4; ++mi)
; #pragma unroll
;       for (int ni = 0; ni < 2; ++ni)
;         acc[mi][ni] = SWAP ? MFMA(fb[buf][ni], fa[buf][mi], acc[mi][ni]) : MFMA(fa[buf][mi], fb[buf][ni], acc[mi][ni]);
;   };
;   auto pat_rd = [&]() {
; #pragma unroll
;     for (int g = 0; g < 6; ++g) {
;       __builtin_amdgcn_sched_group_barrier(0x100, 1, 0);
;       __builtin_amdgcn_sched_group_barrier(0x008, 1, 0);
;     }
;     __builtin_amdgcn_sched_group_barrier(0x008, 2, 0);
;   };
; #pragma unroll 2
;   for (int kt = 0; kt < nk; ++kt) {
;     const char* st = lds + (kt & 1) * 65536;
;     ldfrag(st, 0, 0);
;     mma(1);
;     pat_rd();
;     if (kt + 1 < nk) glds(kt + 1, (kt + 1) & 1);
.Lg8_m246_p0:
	s_waitcnt vmcnt(4)
	s_barrier
	s_add_u32 m0, s100, 0x18000
	s_nop 0
	global_load_lds_dwordx4 v232, s[8:9]
	v_add_u32_e32 v232, 0x80, v232
	s_add_u32 m0, s100, 0x1a000
	s_nop 0
	global_load_lds_dwordx4 v234, s[8:9]
	v_add_u32_e32 v234, 0x80, v234
	s_add_u32 m0, s100, 0x10000
	s_nop 0
	global_load_lds_dwordx4 v228, s[6:7]
	v_add_u32_e32 v228, 0x80, v228
	s_add_u32 m0, s100, 0x12000
	s_nop 0
	global_load_lds_dwordx4 v230, s[6:7]
	v_add_u32_e32 v230, 0x80, v230
	s_add_u32 m0, s100, 0x1c000
	s_nop 0
	global_load_lds_dwordx4 v233, s[8:9]
	v_add_u32_e32 v233, 0x80, v233
	s_add_u32 m0, s100, 0x1e000
	s_nop 0
	global_load_lds_dwordx4 v235, s[8:9]
	v_add_u32_e32 v235, 0x80, v235
	s_waitcnt vmcnt(6)
	s_barrier
.Lg8_m246:
	v_add3_u32 v242, v241, v236, 0
	v_add3_u32 v243, v241, v237, 0
	v_add3_u32 v244, v241, v238, 0
	v_add3_u32 v245, v241, v239, 0
	ds_read_b128 v[162:165], v242 offset:32768
	ds_read_b128 v[166:169], v243 offset:32768
	ds_read_b128 v[170:173], v244 offset:32768
	ds_read_b128 v[174:177], v245 offset:32768
	v_add3_u32 v242, v240, v236, 0
	v_add3_u32 v243, v240, v237, 0
	v_add3_u32 v244, v240, v238, 0
	v_add3_u32 v245, v240, v239, 0
	ds_read_b128 v[130:133], v242
	ds_read_b128 v[134:137], v243
	ds_read_b128 v[138:141], v244
	ds_read_b128 v[142:145], v245
	ds_read_b128 v[146:149], v242 offset:4096
	ds_read_b128 v[150:153], v243 offset:4096
	ds_read_b128 v[154:157], v244 offset:4096
	ds_read_b128 v[158:161], v245 offset:4096
	s_add_u32 m0, s100, 0x14000
	s_nop 0
	global_load_lds_dwordx4 v229, s[6:7]
	v_add_u32_e32 v229, 0x80, v229
	s_add_u32 m0, s100, 0x16000
	s_nop 0
	global_load_lds_dwordx4 v231, s[6:7]
	v_add_u32_e32 v231, 0x80, v231
	s_waitcnt lgkmcnt(8)
	s_barrier
	s_waitcnt lgkmcnt(0)
	v_mfma_f32_32x32x16_bf16 v[114:129], v[162:165], v[130:133], v[114:129]
	v_mfma_f32_32x32x16_bf16 v[82:97], v[162:165], v[146:149], v[82:97]
	v_mfma_f32_32x32x16_bf16 v[114:129], v[166:169], v[134:137], v[114:129]
	v_mfma_f32_32x32x16_bf16 v[82:97], v[166:169], v[150:153], v[82:97]
	v_mfma_f32_32x32x16_bf16 v[114:129], v[170:173], v[138:141], v[114:129]
	v_mfma_f32_32x32x16_bf16 v[82:97], v[170:173], v[154:157], v[82:97]
	v_mfma_f32_32x32x16_bf16 v[114:129], v[174:177], v[142:145], v[114:129]
	v_mfma_f32_32x32x16_bf16 v[82:97], v[174:177], v[158:161], v[82:97]
	s_barrier
	v_add3_u32 v242, v241, v236, 0
	v_add3_u32 v243, v241, v237, 0
	v_add3_u32 v244, v241, v238, 0
	v_add3_u32 v245, v241, v239, 0
	ds_read_b128 v[180:183], v242 offset:49152
	ds_read_b128 v[186:189], v243 offset:49152
	ds_read_b128 v[190:193], v244 offset:49152
	ds_read_b128 v[194:197], v245 offset:49152
	s_add_u32 m0, s100, 0x8000
	s_nop 0
	global_load_lds_dwordx4 v232, s[8:9]
	v_add_u32_e32 v232, 0x80, v232
	s_add_u32 m0, s100, 0xa000
	s_nop 0
	global_load_lds_dwordx4 v234, s[8:9]
	v_add_u32_e32 v234, 0x80, v234
	s_barrier
	s_waitcnt lgkmcnt(0)
	v_mfma_f32_32x32x16_bf16 v[98:113], v[180:183], v[130:133], v[98:113]
	v_mfma_f32_32x32x16_bf16 v[66:81], v[180:183], v[146:149], v[66:81]
	v_mfma_f32_32x32x16_bf16 v[98:113], v[186:189], v[134:137], v[98:113]
	v_mfma_f32_32x32x16_bf16 v[66:81], v[186:189], v[150:153], v[66:81]
	v_mfma_f32_32x32x16_bf16 v[98:113], v[190:193], v[138:141], v[98:113]
	v_mfma_f32_32x32x16_bf16 v[66:81], v[190:193], v[154:157], v[66:81]
	v_mfma_f32_32x32x16_bf16 v[98:113], v[194:197], v[142:145], v[98:113]
	v_mfma_f32_32x32x16_bf16 v[66:81], v[194:197], v[158:161], v[66:81]
	s_barrier
	v_add3_u32 v242, v240, v236, 0
	v_add3_u32 v243, v240, v237, 0
	v_add3_u32 v244, v240, v238, 0
	v_add3_u32 v245, v240, v239, 0
	ds_read_b128 v[130:133], v242 offset:16384
	ds_read_b128 v[134:137], v243 offset:16384
	ds_read_b128 v[138:141], v244 offset:16384
	ds_read_b128 v[142:145], v245 offset:16384
	ds_read_b128 v[146:149], v242 offset:20480
	ds_read_b128 v[150:153], v243 offset:20480
	ds_read_b128 v[154:157], v244 offset:20480
	ds_read_b128 v[158:161], v245 offset:20480
	s_add_u32 m0, s100, 0x0
	s_nop 0
	global_load_lds_dwordx4 v228, s[6:7]
	v_add_u32_e32 v228, 0x80, v228
	s_add_u32 m0, s100, 0x2000
	s_nop 0
	global_load_lds_dwordx4 v230, s[6:7]
	v_add_u32_e32 v230, 0x80, v230
	s_barrier
	s_waitcnt lgkmcnt(0)
	v_mfma_f32_32x32x16_bf16 v[50:65], v[162:165], v[130:133], v[50:65]
	v_mfma_f32_32x32x16_bf16 v[18:33], v[162:165], v[146:149], v[18:33]
	v_mfma_f32_32x32x16_bf16 v[50:65], v[166:169], v[134:137], v[50:65]
	v_mfma_f32_32x32x16_bf16 v[18:33], v[166:169], v[150:153], v[18:33]
	v_mfma_f32_32x32x16_bf16 v[50:65], v[170:173], v[138:141], v[50:65]
	v_mfma_f32_32x32x16_bf16 v[18:33], v[170:173], v[154:157], v[18:33]
	v_mfma_f32_32x32x16_bf16 v[50:65], v[174:177], v[142:145], v[50:65]
	v_mfma_f32_32x32x16_bf16 v[18:33], v[174:177], v[158:161], v[18:33]
	s_barrier
	s_add_u32 m0, s100, 0xc000
	s_nop 0
	global_load_lds_dwordx4 v233, s[8:9]
	v_add_u32_e32 v233, 0x80, v233
	s_add_u32 m0, s100, 0xe000
	s_nop 0
	global_load_lds_dwordx4 v235, s[8:9]
	v_add_u32_e32 v235, 0x80, v235
	s_waitcnt vmcnt(6)
	s_barrier
	v_mfma_f32_32x32x16_bf16 v[34:49], v[180:183], v[130:133], v[34:49]
	v_mfma_f32_32x32x16_bf16 v[2:17], v[180:183], v[146:149], v[2:17]
	v_mfma_f32_32x32x16_bf16 v[34:49], v[186:189], v[134:137], v[34:49]
	v_mfma_f32_32x32x16_bf16 v[2:17], v[186:189], v[150:153], v[2:17]
	v_mfma_f32_32x32x16_bf16 v[34:49], v[190:193], v[138:141], v[34:49]
	v_mfma_f32_32x32x16_bf16 v[2:17], v[190:193], v[154:157], v[2:17]
	v_mfma_f32_32x32x16_bf16 v[34:49], v[194:197], v[142:145], v[34:49]
	v_mfma_f32_32x32x16_bf16 v[2:17], v[194:197], v[158:161], v[2:17]
	s_barrier
; template <bool SWAP>
; DI void gemm_mainloop(f32x16 (&acc)[4][2], const u16* __restrict__ A, int lda, int rlo, int rhi,
;                       const u16* __restrict__ B, int ldb, int K, char* lds, const u16* zero_line) {
;     ...
; #pragma unroll 2
;   for (int kt = 0; kt < nk; ++kt) {
;     const char* st = lds + (kt & 1) * 65536;
;     ldfrag(st, 0, 0);
;     mma(1);
;     pat_rd();
;     if (kt + 1 < nk) glds(kt + 1, (kt + 1) & 1);
;     ldfrag(st, 1, 1);
;     mma(0);
;     pat_rd();
;     ldfrag(st, 2, 0);
;     mma(1);
;     pat_rd();
;     ldfrag(st, 3, 1);
;     mma(0);
;     pat_rd();
;     asm volatile("s_waitcnt vmcnt(0)" ::: "memory");
;     __syncthreads();
;   }
;   mma(1);
	v_add3_u32 v242, v241, v236, s10
	v_add3_u32 v243, v241, v237, s10
	v_add3_u32 v244, v241, v238, s10
	v_add3_u32 v245, v241, v239, s10
	ds_read_b128 v[162:165], v242 offset:32768
	ds_read_b128 v[166:169], v243 offset:32768
	ds_read_b128 v[170:173], v244 offset:32768
	ds_read_b128 v[174:177], v245 offset:32768
	v_add3_u32 v242, v240, v236, s10
	v_add3_u32 v243, v240, v237, s10
	v_add3_u32 v244, v240, v238, s10
	v_add3_u32 v245, v240, v239, s10
	ds_read_b128 v[130:133], v242
	ds_read_b128 v[134:137], v243
	ds_read_b128 v[138:141], v244
	ds_read_b128 v[142:145], v245
	ds_read_b128 v[146:149], v242 offset:4096
	ds_read_b128 v[150:153], v243 offset:4096
	ds_read_b128 v[154:157], v244 offset:4096
	ds_read_b128 v[158:161], v245 offset:4096
	s_add_u32 m0, s100, 0x4000
	s_nop 0
	global_load_lds_dwordx4 v229, s[6:7]
	v_add_u32_e32 v229, 0x80, v229
	s_add_u32 m0, s100, 0x6000
	s_nop 0
	global_load_lds_dwordx4 v231, s[6:7]
	v_add_u32_e32 v231, 0x80, v231
	s_waitcnt lgkmcnt(8)
	s_barrier
	s_waitcnt lgkmcnt(0)
	v_mfma_f32_32x32x16_bf16 v[114:129], v[162:165], v[130:133], v[114:129]
	v_mfma_f32_32x32x16_bf16 v[82:97], v[162:165], v[146:149], v[82:97]
	v_mfma_f32_32x32x16_bf16 v[114:129], v[166:169], v[134:137], v[114:129]
	v_mfma_f32_32x32x16_bf16 v[82:97], v[166:169], v[150:153], v[82:97]
	v_mfma_f32_32x32x16_bf16 v[114:129], v[170:173], v[138:141], v[114:129]
	v_mfma_f32_32x32x16_bf16 v[82:97], v[170:173], v[154:157], v[82:97]
	v_mfma_f32_32x32x16_bf16 v[114:129], v[174:177], v[142:145], v[114:129]
	v_mfma_f32_32x32x16_bf16 v[82:97], v[174:177], v[158:161], v[82:97]
	s_barrier
	v_add3_u32 v242, v241, v236, s10
	v_add3_u32 v243, v241, v237, s10
	v_add3_u32 v244, v241, v238, s10
	v_add3_u32 v245, v241, v239, s10
	ds_read_b128 v[180:183], v242 offset:49152
	ds_read_b128 v[186:189], v243 offset:49152
	ds_read_b128 v[190:193], v244 offset:49152
	ds_read_b128 v[194:197], v245 offset:49152
	s_add_u32 m0, s100, 0x18000
	s_nop 0
	global_load_lds_dwordx4 v232, s[8:9]
	v_add_u32_e32 v232, 0x80, v232
	s_add_u32 m0, s100, 0x1a000
	s_nop 0
	global_load_lds_dwordx4 v234, s[8:9]
	v_add_u32_e32 v234, 0x80, v234
	s_barrier
	s_waitcnt lgkmcnt(0)
	v_mfma_f32_32x32x16_bf16 v[98:113], v[180:183], v[130:133], v[98:113]
	v_mfma_f32_32x32x16_bf16 v[66:81], v[180:183], v[146:149], v[66:81]
	v_mfma_f32_32x32x16_bf16 v[98:113], v[186:189], v[134:137], v[98:113]
	v_mfma_f32_32x32x16_bf16 v[66:81], v[186:189], v[150:153], v[66:81]
	v_mfma_f32_32x32x16_bf16 v[98:113], v[190:193], v[138:141], v[98:113]
	v_mfma_f32_32x32x16_bf16 v[66:81], v[190:193], v[154:157], v[66:81]
	v_mfma_f32_32x32x16_bf16 v[98:113], v[194:197], v[142:145], v[98:113]
	v_mfma_f32_32x32x16_bf16 v[66:81], v[194:197], v[158:161], v[66:81]
	s_barrier
	v_add3_u32 v242, v240, v236, s10
	v_add3_u32 v243, v240, v237, s10
	v_add3_u32 v244, v240, v238, s10
	v_add3_u32 v245, v240, v239, s10
	ds_read_b128 v[130:133], v242 offset:16384
	ds_read_b128 v[134:137], v243 offset:16384
	ds_read_b128 v[138:141], v244 offset:16384
	ds_read_b128 v[142:145], v245 offset:16384
	ds_read_b128 v[146:149], v242 offset:20480
	ds_read_b128 v[150:153], v243 offset:20480
	ds_read_b128 v[154:157], v244 offset:20480
	ds_read_b128 v[158:161], v245 offset:20480
	s_add_u32 m0, s100, 0x10000
	s_nop 0
	global_load_lds_dwordx4 v228, s[6:7]
	v_add_u32_e32 v228, 0x80, v228
	s_add_u32 m0, s100, 0x12000
	s_nop 0
	global_load_lds_dwordx4 v230, s[6:7]
	v_add_u32_e32 v230, 0x80, v230
	s_barrier
	s_waitcnt lgkmcnt(0)
	v_mfma_f32_32x32x16_bf16 v[50:65], v[162:165], v[130:133], v[50:65]
	v_mfma_f32_32x32x16_bf16 v[18:33], v[162:165], v[146:149], v[18:33]
	v_mfma_f32_32x32x16_bf16 v[50:65], v[166:169], v[134:137], v[50:65]
	v_mfma_f32_32x32x16_bf16 v[18:33], v[166:169], v[150:153], v[18:33]
	v_mfma_f32_32x32x16_bf16 v[50:65], v[170:173], v[138:141], v[50:65]
	v_mfma_f32_32x32x16_bf16 v[18:33], v[170:173], v[154:157], v[18:33]
	v_mfma_f32_32x32x16_bf16 v[50:65], v[174:177], v[142:145], v[50:65]
	v_mfma_f32_32x32x16_bf16 v[18:33], v[174:177], v[158:161], v[18:33]
	s_barrier
	s_add_u32 m0, s100, 0x1c000
	s_nop 0
	global_load_lds_dwordx4 v233, s[8:9]
	v_add_u32_e32 v233, 0x80, v233
	s_add_u32 m0, s100, 0x1e000
	s_nop 0
	global_load_lds_dwordx4 v235, s[8:9]
	v_add_u32_e32 v235, 0x80, v235
	s_waitcnt vmcnt(6)
	s_barrier
	v_mfma_f32_32x32x16_bf16 v[34:49], v[180:183], v[130:133], v[34:49]
	v_mfma_f32_32x32x16_bf16 v[2:17], v[180:183], v[146:149], v[2:17]
	v_mfma_f32_32x32x16_bf16 v[34:49], v[186:189], v[134:137], v[34:49]
	v_mfma_f32_32x32x16_bf16 v[2:17], v[186:189], v[150:153], v[2:17]
	v_mfma_f32_32x32x16_bf16 v[34:49], v[190:193], v[138:141], v[34:49]
	v_mfma_f32_32x32x16_bf16 v[2:17], v[190:193], v[154:157], v[2:17]
	v_mfma_f32_32x32x16_bf16 v[34:49], v[194:197], v[142:145], v[34:49]
	v_mfma_f32_32x32x16_bf16 v[2:17], v[194:197], v[158:161], v[2:17]
	s_barrier
	s_add_i32 s11, s11, 2
	s_cmp_lt_u32 s11, s25
	s_cbranch_scc1 .Lg8_m246
	v_add3_u32 v242, v241, v236, 0
	v_add3_u32 v243, v241, v237, 0
	v_add3_u32 v244, v241, v238, 0
	v_add3_u32 v245, v241, v239, 0
	ds_read_b128 v[162:165], v242 offset:32768
	ds_read_b128 v[166:169], v243 offset:32768
	ds_read_b128 v[170:173], v244 offset:32768
	ds_read_b128 v[174:177], v245 offset:32768
	v_add3_u32 v242, v240, v236, 0
	v_add3_u32 v243, v240, v237, 0
	v_add3_u32 v244, v240, v238, 0
	v_add3_u32 v245, v240, v239, 0
	ds_read_b128 v[130:133], v242
	ds_read_b128 v[134:137], v243
	ds_read_b128 v[138:141], v244
	ds_read_b128 v[142:145], v245
	ds_read_b128 v[146:149], v242 offset:4096
	ds_read_b128 v[150:153], v243 offset:4096
	ds_read_b128 v[154:157], v244 offset:4096
	ds_read_b128 v[158:161], v245 offset:4096
	s_add_u32 m0, s100, 0x14000
	s_nop 0
	global_load_lds_dwordx4 v229, s[6:7]
	v_add_u32_e32 v229, 0x80, v229
	s_add_u32 m0, s100, 0x16000
	s_nop 0
	global_load_lds_dwordx4 v231, s[6:7]
	v_add_u32_e32 v231, 0x80, v231
	s_barrier
; template <bool SWAP>
; DI void gemm_mainloop(f32x16 (&acc)[4][2], const u16* __restrict__ A, int lda, int rlo, int rhi,
;                       const u16* __restrict__ B, int ldb, int K, char* lds, const u16* zero_line) {
;     ...
; #pragma unroll 2
;   for (int kt = 0; kt < nk; ++kt) {
;     const char* st = lds + (kt & 1) * 65536;
;     ldfrag(st, 0, 0);
;     mma(1);
;     pat_rd();
;     if (kt + 1 < nk) glds(kt + 1, (kt + 1) & 1);
;     ldfrag(st, 1, 1);
;     mma(0);
;     pat_rd();
;     ldfrag(st, 2, 0);
;     mma(1);
;     pat_rd();
;     ldfrag(st, 3, 1);
;     mma(0);
;     pat_rd();
;     asm volatile("s_waitcnt vmcnt(0)" ::: "memory");
;     __syncthreads();
;   }
;   mma(1);
	s_waitcnt lgkmcnt(0)
	v_mfma_f32_32x32x16_bf16 v[114:129], v[162:165], v[130:133], v[114:129]
	v_mfma_f32_32x32x16_bf16 v[82:97], v[162:165], v[146:149], v[82:97]
	v_mfma_f32_32x32x16_bf16 v[114:129], v[166:169], v[134:137], v[114:129]
	v_mfma_f32_32x32x16_bf16 v[82:97], v[166:169], v[150:153], v[82:97]
	v_mfma_f32_32x32x16_bf16 v[114:129], v[170:173], v[138:141], v[114:129]
	v_mfma_f32_32x32x16_bf16 v[82:97], v[170:173], v[154:157], v[82:97]
	v_mfma_f32_32x32x16_bf16 v[114:129], v[174:177], v[142:145], v[114:129]
	v_mfma_f32_32x32x16_bf16 v[82:97], v[174:177], v[158:161], v[82:97]
	s_barrier
	v_add3_u32 v242, v241, v236, 0
	v_add3_u32 v243, v241, v237, 0
	v_add3_u32 v244, v241, v238, 0
	v_add3_u32 v245, v241, v239, 0
	ds_read_b128 v[180:183], v242 offset:49152
	ds_read_b128 v[186:189], v243 offset:49152
	ds_read_b128 v[190:193], v244 offset:49152
	ds_read_b128 v[194:197], v245 offset:49152
	s_barrier
	s_waitcnt lgkmcnt(0)
	v_mfma_f32_32x32x16_bf16 v[98:113], v[180:183], v[130:133], v[98:113]
	v_mfma_f32_32x32x16_bf16 v[66:81], v[180:183], v[146:149], v[66:81]
	v_mfma_f32_32x32x16_bf16 v[98:113], v[186:189], v[134:137], v[98:113]
	v_mfma_f32_32x32x16_bf16 v[66:81], v[186:189], v[150:153], v[66:81]
	v_mfma_f32_32x32x16_bf16 v[98:113], v[190:193], v[138:141], v[98:113]
	v_mfma_f32_32x32x16_bf16 v[66:81], v[190:193], v[154:157], v[66:81]
	v_mfma_f32_32x32x16_bf16 v[98:113], v[194:197], v[142:145], v[98:113]
	v_mfma_f32_32x32x16_bf16 v[66:81], v[194:197], v[158:161], v[66:81]
	s_barrier
	v_add3_u32 v242, v240, v236, 0
	v_add3_u32 v243, v240, v237, 0
	v_add3_u32 v244, v240, v238, 0
	v_add3_u32 v245, v240, v239, 0
	ds_read_b128 v[130:133], v242 offset:16384
	ds_read_b128 v[134:137], v243 offset:16384
	ds_read_b128 v[138:141], v244 offset:16384
	ds_read_b128 v[142:145], v245 offset:16384
	ds_read_b128 v[146:149], v242 offset:20480
	ds_read_b128 v[150:153], v243 offset:20480
	ds_read_b128 v[154:157], v244 offset:20480
	ds_read_b128 v[158:161], v245 offset:20480
	s_waitcnt vmcnt(4)
	s_barrier
	s_waitcnt lgkmcnt(0)
	v_mfma_f32_32x32x16_bf16 v[50:65], v[162:165], v[130:133], v[50:65]
	v_mfma_f32_32x32x16_bf16 v[18:33], v[162:165], v[146:149], v[18:33]
	v_mfma_f32_32x32x16_bf16 v[50:65], v[166:169], v[134:137], v[50:65]
	v_mfma_f32_32x32x16_bf16 v[18:33], v[166:169], v[150:153], v[18:33]
	v_mfma_f32_32x32x16_bf16 v[50:65], v[170:173], v[138:141], v[50:65]
	v_mfma_f32_32x32x16_bf16 v[18:33], v[170:173], v[154:157], v[18:33]
	v_mfma_f32_32x32x16_bf16 v[50:65], v[174:177], v[142:145], v[50:65]
	v_mfma_f32_32x32x16_bf16 v[18:33], v[174:177], v[158:161], v[18:33]
	v_mfma_f32_32x32x16_bf16 v[34:49], v[180:183], v[130:133], v[34:49]
	v_mfma_f32_32x32x16_bf16 v[2:17], v[180:183], v[146:149], v[2:17]
	v_mfma_f32_32x32x16_bf16 v[34:49], v[186:189], v[134:137], v[34:49]
	v_mfma_f32_32x32x16_bf16 v[2:17], v[186:189], v[150:153], v[2:17]
	v_mfma_f32_32x32x16_bf16 v[34:49], v[190:193], v[138:141], v[34:49]
	v_mfma_f32_32x32x16_bf16 v[2:17], v[190:193], v[154:157], v[2:17]
	v_mfma_f32_32x32x16_bf16 v[34:49], v[194:197], v[142:145], v[34:49]
	v_mfma_f32_32x32x16_bf16 v[2:17], v[194:197], v[158:161], v[2:17]
	s_barrier
	v_add3_u32 v242, v241, v236, s10
	v_add3_u32 v243, v241, v237, s10
	v_add3_u32 v244, v241, v238, s10
	v_add3_u32 v245, v241, v239, s10
	ds_read_b128 v[162:165], v242 offset:32768
	ds_read_b128 v[166:169], v243 offset:32768
	ds_read_b128 v[170:173], v244 offset:32768
	ds_read_b128 v[174:177], v245 offset:32768
	v_add3_u32 v242, v240, v236, s10
	v_add3_u32 v243, v240, v237, s10
	v_add3_u32 v244, v240, v238, s10
	v_add3_u32 v245, v240, v239, s10
	ds_read_b128 v[130:133], v242
	ds_read_b128 v[134:137], v243
	ds_read_b128 v[138:141], v244
	ds_read_b128 v[142:145], v245
	ds_read_b128 v[146:149], v242 offset:4096
	ds_read_b128 v[150:153], v243 offset:4096
	ds_read_b128 v[154:157], v244 offset:4096
	ds_read_b128 v[158:161], v245 offset:4096
	s_waitcnt vmcnt(2)
	s_barrier
	s_waitcnt lgkmcnt(0)
	v_mfma_f32_32x32x16_bf16 v[114:129], v[162:165], v[130:133], v[114:129]
	v_mfma_f32_32x32x16_bf16 v[82:97], v[162:165], v[146:149], v[82:97]
	v_mfma_f32_32x32x16_bf16 v[114:129], v[166:169], v[134:137], v[114:129]
	v_mfma_f32_32x32x16_bf16 v[82:97], v[166:169], v[150:153], v[82:97]
	v_mfma_f32_32x32x16_bf16 v[114:129], v[170:173], v[138:141], v[114:129]
	v_mfma_f32_32x32x16_bf16 v[82:97], v[170:173], v[154:157], v[82:97]
	v_mfma_f32_32x32x16_bf16 v[114:129], v[174:177], v[142:145], v[114:129]
	v_mfma_f32_32x32x16_bf16 v[82:97], v[174:177], v[158:161], v[82:97]
	s_barrier
	v_add3_u32 v242, v241, v236, s10
	v_add3_u32 v243, v241, v237, s10
	v_add3_u32 v244, v241, v238, s10
	v_add3_u32 v245, v241, v239, s10
	ds_read_b128 v[180:183], v242 offset:49152
	ds_read_b128 v[186:189], v243 offset:49152
	ds_read_b128 v[190:193], v244 offset:49152
	ds_read_b128 v[194:197], v245 offset:49152
	s_waitcnt vmcnt(0)
	s_barrier
	s_waitcnt lgkmcnt(0)
	v_mfma_f32_32x32x16_bf16 v[98:113], v[180:183], v[130:133], v[98:113]
	v_mfma_f32_32x32x16_bf16 v[66:81], v[180:183], v[146:149], v[66:81]
	v_mfma_f32_32x32x16_bf16 v[98:113], v[186:189], v[134:137], v[98:113]
	v_mfma_f32_32x32x16_bf16 v[66:81], v[186:189], v[150:153], v[66:81]
	v_mfma_f32_32x32x16_bf16 v[98:113], v[190:193], v[138:141], v[98:113]
	v_mfma_f32_32x32x16_bf16 v[66:81], v[190:193], v[154:157], v[66:81]
	v_mfma_f32_32x32x16_bf16 v[98:113], v[194:197], v[142:145], v[98:113]
	v_mfma_f32_32x32x16_bf16 v[66:81], v[194:197], v[158:161], v[66:81]
	s_barrier
; template <bool SWAP>
; DI void gemm_mainloop(f32x16 (&acc)[4][2], const u16* __restrict__ A, int lda, int rlo, int rhi,
;                       const u16* __restrict__ B, int ldb, int K, char* lds, const u16* zero_line) {
;     ...
;     ldfrag(st, 2, 0);
;     mma(1);
;     pat_rd();
;     ldfrag(st, 3, 1);
;     mma(0);
;     pat_rd();
;     asm volatile("s_waitcnt vmcnt(0)" ::: "memory");
;     __syncthreads();
;   }
;   mma(1);
	v_add3_u32 v242, v240, v236, s10
	v_add3_u32 v243, v240, v237, s10
	v_add3_u32 v244, v240, v238, s10
	v_add3_u32 v245, v240, v239, s10
	ds_read_b128 v[130:133], v242 offset:16384
	ds_read_b128 v[134:137], v243 offset:16384
	ds_read_b128 v[138:141], v244 offset:16384
	ds_read_b128 v[142:145], v245 offset:16384
	ds_read_b128 v[146:149], v242 offset:20480
	ds_read_b128 v[150:153], v243 offset:20480
	ds_read_b128 v[154:157], v244 offset:20480
	ds_read_b128 v[158:161], v245 offset:20480
	s_barrier
	s_waitcnt lgkmcnt(0)
	v_mfma_f32_32x32x16_bf16 v[50:65], v[162:165], v[130:133], v[50:65]
	v_mfma_f32_32x32x16_bf16 v[18:33], v[162:165], v[146:149], v[18:33]
	v_mfma_f32_32x32x16_bf16 v[50:65], v[166:169], v[134:137], v[50:65]
	v_mfma_f32_32x32x16_bf16 v[18:33], v[166:169], v[150:153], v[18:33]
	v_mfma_f32_32x32x16_bf16 v[50:65], v[170:173], v[138:141], v[50:65]
	v_mfma_f32_32x32x16_bf16 v[18:33], v[170:173], v[154:157], v[18:33]
	v_mfma_f32_32x32x16_bf16 v[50:65], v[174:177], v[142:145], v[50:65]
	v_mfma_f32_32x32x16_bf16 v[18:33], v[174:177], v[158:161], v[18:33]
	v_mfma_f32_32x32x16_bf16 v[34:49], v[180:183], v[130:133], v[34:49]
	v_mfma_f32_32x32x16_bf16 v[2:17], v[180:183], v[146:149], v[2:17]
	v_mfma_f32_32x32x16_bf16 v[34:49], v[186:189], v[134:137], v[34:49]
	v_mfma_f32_32x32x16_bf16 v[2:17], v[186:189], v[150:153], v[2:17]
	v_mfma_f32_32x32x16_bf16 v[34:49], v[190:193], v[138:141], v[34:49]
	v_mfma_f32_32x32x16_bf16 v[2:17], v[190:193], v[154:157], v[2:17]
	v_mfma_f32_32x32x16_bf16 v[34:49], v[194:197], v[142:145], v[34:49]
	v_mfma_f32_32x32x16_bf16 v[2:17], v[194:197], v[158:161], v[2:17]
	s_barrier
	s_cmp_eq_u32 s101, 0
	s_cbranch_scc0 .Lg8_m246_p1
	s_barrier
; template <int EPI>
; DI void phase_gemm(const Params& p, const GemmArgs& ga, char* lds) {
;     ...
;     const int n0w = nt * 256 + wn * 64;
;     if (EPI == EPI_M) {
;       u16* mo = ga.Mout + (size_t)(tokbase + pos0 + wm * 128 + r) * DM + n0w + 8 * h;
; #pragma unroll
;       for (int mi = 0; mi < 4; ++mi)
; #pragma unroll
;         for (int ni = 0; ni < 2; ++ni)
; #pragma unroll
;           for (int jp = 0; jp < 2; ++jp) {
;             u32x2 X = {pk_bf16(acc[mi][ni][8 * jp], acc[mi][ni][8 * jp + 1]), pk_bf16(acc[mi][ni][8 * jp + 2], acc[mi][ni][8 * jp + 3])};
;             u32x2 Y = {pk_bf16(acc[mi][ni][8 * jp + 4], acc[mi][ni][8 * jp + 5]), pk_bf16(acc[mi][ni][8 * jp + 6], acc[mi][ni][8 * jp + 7])};
;             half_swap(X, Y);
;             u32x4 v = {X.x, X.y, Y.x, Y.y};
;             *(u32x4*)(mo + (size_t)(mi * 32) * DM + ni * 32 + 16 * jp) = v;
;           }
.Lg8_m246_p1:
	s_nop 7
	s_nop 7
	v_add_u32_e32 v0, s35, v203
	v_add_u32_e32 v180, s35, v202
	v_add_u32_e32 v162, v0, v228
	v_add_u32_e32 v166, v180, v228
	s_mov_b32 s6, 0x10000
	s_mov_b64 s[40:41], 0x3838900
	s_mov_b64 s[38:39], 0x3858900
	s_mov_b64 s[36:37], 0x27c0080
	v_add_u32_e32 v146, v0, v227
	s_waitcnt lgkmcnt(2)
	s_waitcnt lgkmcnt(2)
	v_add_u32_e32 v158, v180, v227
	v_add_u32_e32 v166, v0, v201
	v_add_u32_e32 v0, v0, v179
	s_waitcnt lgkmcnt(2)
	s_waitcnt lgkmcnt(2)
	v_add_u32_e32 v130, v180, v201
	s_waitcnt lgkmcnt(2)
	s_waitcnt lgkmcnt(2)
	v_add_u32_e32 v0, v180, v179
	v_mov_b32_e32 v179, v1
	v_add_u32_e32 v152, s34, v200
	v_ashrrev_i32_e32 v153, 31, v152
	v_or_b32_e32 v150, s24, v185
	v_lshlrev_b64 v[152:153], 11, v[152:153]
	v_lshl_add_u64 v[152:153], s[14:15], 0, v[152:153]
	v_ashrrev_i32_e32 v151, 31, v150
	v_lshl_add_u64 v[150:151], v[150:151], 1, v[152:153]
	v_lshl_add_u64 v[150:151], v[150:151], 0, v[178:179]
	s_waitcnt vmcnt(0)
	s_waitcnt lgkmcnt(0)
	s_barrier
	s_nop 10
	v_cvt_pk_bf16_f32 v82, v82, v83
	v_cvt_pk_bf16_f32 v83, v84, v85
	v_cvt_pk_bf16_f32 v84, v86, v87
	v_add_co_u32_e32 v86, vcc, s6, v150
	s_mov_b32 s6, 0x30000
	s_nop 0
	v_addc_co_u32_e32 v87, vcc, 0, v151, vcc
	v_cvt_pk_bf16_f32 v50, v50, v51
	v_cvt_pk_bf16_f32 v51, v52, v53
	v_cvt_pk_bf16_f32 v52, v54, v55
	v_add_co_u32_e32 v54, vcc, s84, v150
	v_cvt_pk_bf16_f32 v85, v88, v89
	s_nop 0
	v_addc_co_u32_e32 v55, vcc, 0, v151, vcc
	s_nop 3
	v_cvt_pk_bf16_f32 v114, v114, v115
	v_cvt_pk_bf16_f32 v115, v116, v117
	v_cvt_pk_bf16_f32 v116, v118, v119
	v_cvt_pk_bf16_f32 v117, v120, v121
	v_cvt_pk_bf16_f32 v53, v56, v57
	v_permlane32_swap_b32_e32 v114, v116
	s_nop 0
	v_cvt_pk_bf16_f32 v98, v98, v99
	v_cvt_pk_bf16_f32 v99, v100, v101
	v_cvt_pk_bf16_f32 v100, v102, v103
	v_cvt_pk_bf16_f32 v101, v104, v105
	v_permlane32_swap_b32_e32 v115, v117
	v_permlane32_swap_b32_e32 v98, v100
	s_nop 3
	v_cvt_pk_bf16_f32 v66, v66, v67
	v_cvt_pk_bf16_f32 v67, v68, v69
	v_cvt_pk_bf16_f32 v68, v70, v71
	v_cvt_pk_bf16_f32 v69, v72, v73
	v_permlane32_swap_b32_e32 v99, v101
	v_permlane32_swap_b32_e32 v82, v84
	s_nop 0
	v_cvt_pk_bf16_f32 v34, v34, v35
	v_cvt_pk_bf16_f32 v35, v36, v37
	v_cvt_pk_bf16_f32 v36, v38, v39
	v_cvt_pk_bf16_f32 v37, v40, v41
	v_permlane32_swap_b32_e32 v83, v85
	v_permlane32_swap_b32_e32 v66, v68
	s_nop 3
	v_cvt_pk_bf16_f32 v18, v18, v19
	v_cvt_pk_bf16_f32 v19, v20, v21
	v_cvt_pk_bf16_f32 v20, v22, v23
	v_cvt_pk_bf16_f32 v21, v24, v25
	v_add_co_u32_e32 v22, vcc, s6, v150
	v_permlane32_swap_b32_e32 v67, v69
	s_nop 1
	v_cvt_pk_bf16_f32 v2, v2, v3
	v_cvt_pk_bf16_f32 v3, v4, v5
	v_cvt_pk_bf16_f32 v4, v6, v7
	v_cvt_pk_bf16_f32 v5, v8, v9
	v_permlane32_swap_b32_e32 v50, v52
	v_permlane32_swap_b32_e32 v51, v53
	v_permlane32_swap_b32_e32 v34, v36
	v_permlane32_swap_b32_e32 v35, v37
	v_permlane32_swap_b32_e32 v18, v20
	v_permlane32_swap_b32_e32 v19, v21
	v_addc_co_u32_e32 v23, vcc, 0, v151, vcc
	v_permlane32_swap_b32_e32 v2, v4
	v_permlane32_swap_b32_e32 v3, v5
	global_store_dwordx4 v[150:151], v[114:117], off
	global_store_dwordx4 v[150:151], v[98:101], off offset:64
	global_store_dwordx4 v[86:87], v[82:85], off
	v_cvt_pk_bf16_f32 v114, v122, v123
	v_cvt_pk_bf16_f32 v115, v124, v125
	v_cvt_pk_bf16_f32 v116, v126, v127
	v_cvt_pk_bf16_f32 v117, v128, v129
	v_cvt_pk_bf16_f32 v98, v106, v107
	v_cvt_pk_bf16_f32 v99, v108, v109
	v_cvt_pk_bf16_f32 v100, v110, v111
	v_cvt_pk_bf16_f32 v101, v112, v113
	v_cvt_pk_bf16_f32 v82, v90, v91
	v_cvt_pk_bf16_f32 v83, v92, v93
	v_cvt_pk_bf16_f32 v84, v94, v95
	v_cvt_pk_bf16_f32 v85, v96, v97
	global_store_dwordx4 v[86:87], v[66:69], off offset:64
	global_store_dwordx4 v[54:55], v[50:53], off
	global_store_dwordx4 v[54:55], v[34:37], off offset:64
	v_cvt_pk_bf16_f32 v66, v74, v75
	v_cvt_pk_bf16_f32 v67, v76, v77
	v_cvt_pk_bf16_f32 v68, v78, v79
	v_cvt_pk_bf16_f32 v69, v80, v81
	v_cvt_pk_bf16_f32 v50, v58, v59
	v_cvt_pk_bf16_f32 v51, v60, v61
	v_cvt_pk_bf16_f32 v52, v62, v63
	v_cvt_pk_bf16_f32 v53, v64, v65
	v_cvt_pk_bf16_f32 v34, v42, v43
	v_cvt_pk_bf16_f32 v35, v44, v45
	v_cvt_pk_bf16_f32 v36, v46, v47
	v_cvt_pk_bf16_f32 v37, v48, v49
	global_store_dwordx4 v[22:23], v[18:21], off
	global_store_dwordx4 v[22:23], v[2:5], off offset:64
	v_permlane32_swap_b32_e32 v114, v116
	v_cvt_pk_bf16_f32 v18, v26, v27
	v_cvt_pk_bf16_f32 v19, v28, v29
	v_cvt_pk_bf16_f32 v20, v30, v31
	v_cvt_pk_bf16_f32 v21, v32, v33
	v_cvt_pk_bf16_f32 v2, v10, v11
	v_cvt_pk_bf16_f32 v3, v12, v13
	v_cvt_pk_bf16_f32 v4, v14, v15
	v_cvt_pk_bf16_f32 v5, v16, v17
	v_permlane32_swap_b32_e32 v115, v117
	v_permlane32_swap_b32_e32 v98, v100
	v_permlane32_swap_b32_e32 v99, v101
	v_permlane32_swap_b32_e32 v82, v84
	v_permlane32_swap_b32_e32 v83, v85
	v_permlane32_swap_b32_e32 v66, v68
	v_permlane32_swap_b32_e32 v67, v69
	v_permlane32_swap_b32_e32 v50, v52
	v_permlane32_swap_b32_e32 v51, v53
	v_permlane32_swap_b32_e32 v34, v36
	v_permlane32_swap_b32_e32 v35, v37
	v_permlane32_swap_b32_e32 v18, v20
	v_permlane32_swap_b32_e32 v19, v21
	v_permlane32_swap_b32_e32 v2, v4
	v_permlane32_swap_b32_e32 v3, v5
	global_store_dwordx4 v[150:151], v[114:117], off offset:32
	global_store_dwordx4 v[150:151], v[98:101], off offset:96
	global_store_dwordx4 v[86:87], v[82:85], off offset:32
	global_store_dwordx4 v[86:87], v[66:69], off offset:96
	global_store_dwordx4 v[54:55], v[50:53], off offset:32
	global_store_dwordx4 v[54:55], v[34:37], off offset:96
	global_store_dwordx4 v[22:23], v[18:21], off offset:32
	global_store_dwordx4 v[22:23], v[2:5], off offset:96
	s_branch .LBB0_243
